# SWA: per-head sink value loaded once per CU and kept in an SGPR instead of a global load + full wait at every unit
# speedup vs baseline: 1.0030x; 1.0030x over previous
.LBB0_1957:
	s_or_b64 exec, exec, s[10:11]
	s_mov_b32 s99, 0
	v_mov_b32_e32 v120, v210
	s_waitcnt lgkmcnt(0)
	s_barrier
	s_cmpk_gt_i32 s2, 0x47f
	v_readfirstlane_b32 s4, v120
	s_cbranch_scc1 .LBB0_2108
	s_movk_i32 s3, 0x400
	s_add_u32 s54, s30, 0x5890800
	v_and_b32_e32 v1, 32, v120
	v_cmp_gt_i32_e64 s[10:11], s3, v120
	s_addc_u32 s55, s31, 0
	s_ashr_i32 s3, s4, 7
	s_lshr_b32 s5, s4, 1
	v_and_b32_e32 v2, 31, v120
	s_and_b32 s5, s5, 32
	v_cmp_eq_u32_e32 vcc, 0, v1
	s_lshl_b32 s12, s3, 10
	v_or_b32_e32 v122, s5, v2
	v_cndmask_b32_e64 v127, 0, 1.0, vcc
	s_add_i32 s20, s12, 0
	v_bitop3_b32 v1, s5, 63, v2 bitop3:0x36
	v_cmp_gt_u32_e32 vcc, 16, v2
	v_bitop3_b32 v2, v120, 15, v120 bitop3:0xc
	v_lshl_add_u32 v140, v2, 2, s20
	v_max_i32_e32 v2, 0x200, v120
	v_sub_u32_e32 v2, v2, v120
	v_and_b32_e32 v3, 15, v120
	v_add_u32_e32 v2, 0x1ff, v2
	v_or_b32_e32 v124, 0x4000, v3
	v_lshrrev_b32_e32 v3, 9, v2
	s_load_dwordx2 s[56:57], s[0:1], 0xd0
	v_add_u32_e32 v4, 1, v3
	v_add_u32_e32 v3, -1, v3
	s_movk_i32 s78, 0x1ff
	v_lshrrev_b32_e32 v5, 1, v3
	s_bitcmp0_b32 s4, 6
	v_add_u32_e32 v5, 1, v5
	v_cmp_lt_u32_e64 s[12:13], s78, v2
	v_and_b32_e32 v2, 0xfffffe, v4
	v_lshlrev_b32_e32 v144, 2, v120
	v_mov_b32_e32 v0, 0
	s_cselect_b64 s[58:59], -1, 0
	v_and_b32_e32 v126, 0xff, v120
	v_lshl_add_u32 v141, v2, 9, v120
	v_and_b32_e32 v142, 3, v5
	v_cmp_ne_u32_e64 s[18:19], v4, v2
	v_add_u32_e32 v2, 0, v144
	v_lshl_add_u32 v1, v1, 2, s20
	v_mov_b32_e32 v125, v0
	s_and_b64 s[60:61], s[58:59], vcc
	s_mov_b32 s33, -1
	v_mov_b32_e32 v123, v126
	v_add_u32_e32 v121, 0x200, v120
	v_cmp_lt_u32_e64 s[14:15], 5, v3
	v_and_b32_e32 v143, -4, v5
	v_cmp_ne_u32_e64 s[16:17], 0, v142
	v_add_u32_e32 v145, 0xa000, v2
	v_add_u32_e32 v146, 0xa000, v1
	s_movk_i32 s79, 0xff00
	s_mov_b64 s[62:63], 0x180
	s_movk_i32 s80, 0x110
	s_movk_i32 s81, 0x100
	s_movk_i32 s82, 0x300
	s_movk_i32 s83, 0x900
	s_movk_i32 s85, 0x700
	s_mov_b64 s[64:65], 0x10000
	s_movk_i32 s87, 0x500
	s_mov_b64 s[66:67], 0x20000
	s_mov_b32 s88, 0xf149f2ca
	s_mov_b32 s89, s2
	s_branch .LBB0_1961

.LBB0_1982:
	s_lshl_b32 s4, s46, 2
	s_add_i32 s70, s4, s3
	s_ashr_i32 s71, s70, 31
	s_lshl_b64 s[4:5], s[70:71], 2
	s_waitcnt lgkmcnt(0)
	s_add_u32 s4, s56, s4
	s_addc_u32 s5, s57, s5
	s_cmp_eq_u32 s99, 0x5151
	s_cbranch_scc1 .Lsw_have
	global_load_dword v1, v0, s[4:5]
	s_andn2_b64 vcc, exec, s[20:21]
	s_mov_b64 s[20:21], -1
	s_waitcnt vmcnt(0)
	v_mul_f32_e32 v147, 0x3fb8aa3b, v1
	s_nop 0
	v_readfirstlane_b32 s98, v147
	s_movk_i32 s99, 0x5151
	s_branch .Lsw_join
.Lsw_have:
	s_andn2_b64 vcc, exec, s[20:21]
	s_mov_b64 s[20:21], -1
	v_mov_b32_e32 v147, s98
.Lsw_join:
	s_cbranch_vccnz .LBB0_1989
	s_ashr_i32 s69, s68, 31
	s_lshl_b64 s[4:5], s[68:69], 12
	s_lshl_b32 s20, s47, 6
	s_add_u32 s21, s4, s20
	s_addc_u32 s22, s5, 0
	v_or_b32_e32 v6, s21, v122
	s_sub_i32 s21, 2, s47
	s_cmp_lt_u32 s47, 2
	s_cselect_b32 s47, s21, 0
	s_addk_i32 s20, 0xff80
	s_ashr_i32 s21, s20, 31
	s_add_u32 s4, s4, s20
	s_addc_u32 s5, s5, s21
	s_lshl_b64 s[4:5], s[4:5], 10
	s_add_u32 s4, s50, s4
	s_addc_u32 s5, s51, s5
	s_lshl_b32 s20, s46, 7
	v_mov_b32_e32 v7, s22
	s_add_u32 s74, s4, s20
	s_addc_u32 s75, s5, 0
	v_lshlrev_b64 v[2:3], 11, v[6:7]
	s_lshl_b32 s72, s70, 6
	v_mov_b32_e32 v1, v210
	v_lshl_add_u64 v[2:3], s[42:43], 0, v[2:3]
	s_ashr_i32 s73, s72, 31
	v_lshl_add_u64 v[2:3], s[72:73], 1, v[2:3]
	v_bfe_u32 v12, v1, 5, 1
	v_lshlrev_b32_e32 v128, 4, v12
	v_mov_b32_e32 v129, v0
	v_lshl_add_u64 v[2:3], v[2:3], 0, v[128:129]
	global_load_dwordx4 v[80:83], v[2:3], off
	global_load_dwordx4 v[84:87], v[2:3], off offset:32
	global_load_dwordx4 v[88:91], v[2:3], off offset:64
	global_load_dwordx4 v[92:95], v[2:3], off offset:96
	v_ashrrev_i32_e32 v2, 31, v1
	v_lshrrev_b32_e32 v2, 28, v2
	v_add_u32_e32 v2, v1, v2
	s_lshl_b32 s69, s47, 6
	v_ashrrev_i32_e32 v129, 4, v2
	v_and_b32_e32 v2, -16, v2
	v_sub_u32_e32 v13, v1, v2
	v_add_u32_e32 v2, s69, v129
	v_ashrrev_i32_e32 v3, 31, v2
	v_lshlrev_b64 v[4:5], 10, v[2:3]
	v_cmp_gt_i32_e64 s[20:21], 8, v13
	v_cmp_lt_i32_e32 vcc, 7, v13
	v_lshlrev_b32_e32 v2, 3, v13
	v_lshl_add_u64 v[8:9], s[74:75], 0, v[4:5]
	s_and_saveexec_b64 s[4:5], vcc
	s_xor_b64 s[22:23], exec, s[4:5]
	v_mov_b32_e32 v3, v0
	v_lshl_add_u64 v[4:5], v[2:3], 1, v[8:9]
	v_lshl_add_u64 v[4:5], v[4:5], 0, s[62:63]
	s_or_saveexec_b64 s[22:23], s[22:23]
	v_ashrrev_i32_e32 v3, 31, v2
	s_xor_b64 exec, exec, s[22:23]
	v_lshl_add_u64 v[4:5], v[2:3], 1, v[8:9]
	s_or_b64 exec, exec, s[22:23]
	global_load_dwordx4 v[96:99], v[4:5], off
	v_add_u32_e32 v4, 0x200, v1
	v_ashrrev_i32_e32 v5, 31, v4
	v_lshrrev_b32_e32 v5, 28, v5
	v_add_u32_e32 v5, v4, v5
	v_ashrrev_i32_e32 v148, 4, v5
	v_and_b32_e32 v5, -16, v5
	v_sub_u32_e32 v14, v4, v5
	v_add_u32_e32 v4, s69, v148
	v_ashrrev_i32_e32 v5, 31, v4
	v_lshlrev_b64 v[8:9], 10, v[4:5]
	v_cmp_gt_i32_e64 s[22:23], 8, v14
	v_cmp_lt_i32_e64 s[24:25], 7, v14
	v_lshlrev_b32_e32 v4, 3, v14
	v_lshl_add_u64 v[8:9], s[74:75], 0, v[8:9]
	s_and_saveexec_b64 s[4:5], s[24:25]
	s_xor_b64 s[76:77], exec, s[4:5]
	s_cbranch_execz .LBB0_1990
	v_mov_b32_e32 v5, v0
	v_lshl_add_u64 v[8:9], v[4:5], 1, v[8:9]
	v_lshl_add_u64 v[10:11], v[8:9], 0, s[62:63]
	s_or_saveexec_b64 s[76:77], s[76:77]
	v_ashrrev_i32_e32 v5, 31, v4
	s_xor_b64 exec, exec, s[76:77]
	s_branch .LBB0_1991
